# bundle1 + LRU counted vmcnt at iteration top + attention epilogue gate loads prefetched
# baseline (speedup 1.0000x reference)
.LBB0_366:
	ds_read_b128 v[0:3], v183 offset:1024
	ds_read_b128 v[4:7], v183 offset:1040
	ds_read_b128 v[8:11], v183
	ds_read_b128 v[12:15], v183 offset:16
	ds_read_b128 v[16:19], v183 offset:256
	ds_read_b128 v[20:23], v183 offset:272
	ds_read_b128 v[24:27], v183 offset:512
	ds_read_b128 v[28:31], v183 offset:528
	s_cmp_lt_u32 s97, 5
	s_cbranch_scc1 .Llru_vm0
	s_cmp_eq_u32 s97, 20
	s_cbranch_scc1 .Llru_vm0
	s_waitcnt vmcnt(2)
	s_branch .Llru_vm1

.Llru_vm1:
	ds_read_b128 v[100:103], v183 offset:768
	ds_read_b128 v[104:107], v183 offset:784
	v_lshlrev_b32_e32 v34, 16, v36
	v_and_b32_e32 v35, 0xffff0000, v36
	s_waitcnt lgkmcnt(7)
	v_pk_fma_f32 v[34:35], v[8:9], v[34:35], v[0:1]
	v_lshlrev_b32_e32 v108, 16, v40
	v_and_b32_e32 v109, 0xffff0000, v40
	s_waitcnt lgkmcnt(5)
	v_pk_fma_f32 v[34:35], v[16:17], v[108:109], v[34:35]
	v_lshlrev_b32_e32 v108, 16, v44
	v_and_b32_e32 v109, 0xffff0000, v44
	s_waitcnt lgkmcnt(3)
	v_pk_fma_f32 v[34:35], v[24:25], v[108:109], v[34:35]
	v_lshlrev_b32_e32 v108, 16, v72
	v_and_b32_e32 v109, 0xffff0000, v72
	s_waitcnt lgkmcnt(1)
	v_pk_fma_f32 v[108:109], v[100:101], v[108:109], v[34:35]
	v_lshlrev_b32_e32 v34, 16, v37
	v_and_b32_e32 v35, 0xffff0000, v37
	v_pk_fma_f32 v[34:35], v[10:11], v[34:35], v[2:3]
	v_lshlrev_b32_e32 v110, 16, v41
	v_and_b32_e32 v111, 0xffff0000, v41
	v_pk_fma_f32 v[34:35], v[18:19], v[110:111], v[34:35]
	v_lshlrev_b32_e32 v110, 16, v45
	v_and_b32_e32 v111, 0xffff0000, v45
	v_pk_fma_f32 v[34:35], v[26:27], v[110:111], v[34:35]
	v_lshlrev_b32_e32 v110, 16, v73
	v_and_b32_e32 v111, 0xffff0000, v73
	v_pk_fma_f32 v[110:111], v[102:103], v[110:111], v[34:35]
	v_lshlrev_b32_e32 v34, 16, v38
	v_and_b32_e32 v35, 0xffff0000, v38
	v_pk_fma_f32 v[34:35], v[12:13], v[34:35], v[4:5]
	v_lshlrev_b32_e32 v112, 16, v42
	v_and_b32_e32 v113, 0xffff0000, v42
	v_pk_fma_f32 v[34:35], v[20:21], v[112:113], v[34:35]
	v_lshlrev_b32_e32 v112, 16, v46
	v_and_b32_e32 v113, 0xffff0000, v46
	v_pk_fma_f32 v[34:35], v[28:29], v[112:113], v[34:35]
	v_lshlrev_b32_e32 v112, 16, v74
	v_and_b32_e32 v113, 0xffff0000, v74
	s_waitcnt lgkmcnt(0)
	v_pk_fma_f32 v[112:113], v[104:105], v[112:113], v[34:35]
	v_lshlrev_b32_e32 v34, 16, v39
	v_and_b32_e32 v35, 0xffff0000, v39
	v_pk_fma_f32 v[34:35], v[14:15], v[34:35], v[6:7]
	v_lshlrev_b32_e32 v114, 16, v43
	v_and_b32_e32 v115, 0xffff0000, v43
	v_pk_fma_f32 v[34:35], v[22:23], v[114:115], v[34:35]
	v_lshlrev_b32_e32 v114, 16, v47
	v_and_b32_e32 v115, 0xffff0000, v47
	v_pk_fma_f32 v[34:35], v[30:31], v[114:115], v[34:35]
	v_lshlrev_b32_e32 v114, 16, v75
	v_and_b32_e32 v115, 0xffff0000, v75
	v_pk_fma_f32 v[114:115], v[106:107], v[114:115], v[34:35]
	v_lshlrev_b32_e32 v34, 16, v84
	v_and_b32_e32 v35, 0xffff0000, v84
	v_pk_fma_f32 v[0:1], v[8:9], v[34:35], v[0:1]
	v_lshlrev_b32_e32 v8, 16, v88
	v_and_b32_e32 v9, 0xffff0000, v88
	v_pk_fma_f32 v[0:1], v[16:17], v[8:9], v[0:1]
	v_lshlrev_b32_e32 v8, 16, v92
	v_and_b32_e32 v9, 0xffff0000, v92
	v_pk_fma_f32 v[0:1], v[24:25], v[8:9], v[0:1]
	v_lshlrev_b32_e32 v8, 16, v96
	v_and_b32_e32 v9, 0xffff0000, v96
	v_pk_fma_f32 v[0:1], v[100:101], v[8:9], v[0:1]
	v_lshlrev_b32_e32 v8, 16, v85
	v_and_b32_e32 v9, 0xffff0000, v85
	v_pk_fma_f32 v[2:3], v[10:11], v[8:9], v[2:3]
	v_lshlrev_b32_e32 v8, 16, v89
	v_and_b32_e32 v9, 0xffff0000, v89
	v_pk_fma_f32 v[2:3], v[18:19], v[8:9], v[2:3]
	v_lshlrev_b32_e32 v8, 16, v93
	v_and_b32_e32 v9, 0xffff0000, v93
	v_pk_fma_f32 v[2:3], v[26:27], v[8:9], v[2:3]
	v_lshlrev_b32_e32 v8, 16, v97
	v_and_b32_e32 v9, 0xffff0000, v97
	v_pk_fma_f32 v[2:3], v[102:103], v[8:9], v[2:3]
	v_lshlrev_b32_e32 v8, 16, v86
	v_and_b32_e32 v9, 0xffff0000, v86
	v_pk_fma_f32 v[4:5], v[12:13], v[8:9], v[4:5]
	v_lshlrev_b32_e32 v8, 16, v90
	v_and_b32_e32 v9, 0xffff0000, v90
	v_pk_fma_f32 v[4:5], v[20:21], v[8:9], v[4:5]
	v_lshlrev_b32_e32 v8, 16, v94
	v_and_b32_e32 v9, 0xffff0000, v94
	v_pk_fma_f32 v[4:5], v[28:29], v[8:9], v[4:5]
	v_lshlrev_b32_e32 v8, 16, v98
	v_and_b32_e32 v9, 0xffff0000, v98
	v_pk_fma_f32 v[4:5], v[104:105], v[8:9], v[4:5]
	v_lshlrev_b32_e32 v8, 16, v87
	v_and_b32_e32 v9, 0xffff0000, v87
	v_pk_fma_f32 v[6:7], v[14:15], v[8:9], v[6:7]
	v_lshlrev_b32_e32 v8, 16, v91
	v_and_b32_e32 v9, 0xffff0000, v91
	v_pk_fma_f32 v[6:7], v[22:23], v[8:9], v[6:7]
	v_lshlrev_b32_e32 v8, 16, v95
	v_and_b32_e32 v9, 0xffff0000, v95
	v_pk_fma_f32 v[6:7], v[30:31], v[8:9], v[6:7]
	v_lshlrev_b32_e32 v8, 16, v99
	v_and_b32_e32 v9, 0xffff0000, v99
	v_pk_fma_f32 v[6:7], v[106:107], v[8:9], v[6:7]
	v_cvt_pk_bf16_f32 v8, v108, v109
	v_cvt_pk_bf16_f32 v9, v110, v111
	v_cvt_pk_bf16_f32 v10, v112, v113
	v_cvt_pk_bf16_f32 v11, v114, v115
	s_add_i32 s96, s97, 1
	ds_write_b128 v191, v[108:111]
	ds_write_b128 v191, v[112:115] offset:16
	ds_write_b128 v196, v[8:11] offset:16384
	ds_write_b128 v191, v[0:3] offset:59392
	ds_write_b128 v191, v[4:7] offset:59408
	v_cvt_pk_bf16_f32 v0, v0, v1
	v_cvt_pk_bf16_f32 v1, v2, v3
	v_cvt_pk_bf16_f32 v2, v4, v5
	v_cvt_pk_bf16_f32 v3, v6, v7
	s_cmpk_eq_i32 s68, 0x7c0
	ds_write_b128 v197, v[0:3]
	s_cbranch_scc1 .LBB0_394
	s_and_b32 s36, s96, 0x7b
	s_cmp_lg_u32 s36, 0
	s_cselect_b64 s[36:37], -1, 0
	s_and_b32 s76, s96, 0x5f
	s_cmp_lg_u32 s76, 3
	s_cselect_b64 s[76:77], -1, 0
	s_and_b64 s[36:37], s[36:37], s[76:77]
	s_and_b64 vcc, exec, s[36:37]
	s_cbranch_vccnz .LBB0_375
	s_cmp_lt_u32 s97, 3
	v_add_u32_e32 v0, s68, v180
	s_cselect_b32 s76, 0, 0x100
	s_cselect_b32 s77, s86, 0x900
	v_add_u32_e32 v1, 0x13f, v0
	v_mov_b32_e32 v40, 0
	v_mov_b32_e32 v41, v32
	v_cmp_le_i32_e32 vcc, s76, v1
	v_cmp_gt_i32_e64 s[36:37], s77, v1
	v_mov_b32_e32 v42, v32
	v_mov_b32_e32 v43, v32
	v_mov_b64_e32 v[36:37], v[40:41]
	s_and_b64 s[78:79], vcc, s[36:37]
	v_mov_b64_e32 v[38:39], v[42:43]
	s_and_saveexec_b64 s[36:37], s[78:79]
	s_cbranch_execz .LBB0_370
	global_load_dwordx4 v[36:39], v[176:177], off

.LBB0_432:
	ds_bpermute_b32 v64, v204, v196
	s_mov_b64 s[6:7], -1
	s_waitcnt lgkmcnt(0)
	v_add_f32_e32 v64, v196, v64
	v_div_scale_f32 v65, s[4:5], v64, v64, 1.0
	v_rcp_f32_e32 v66, v65
	v_div_scale_f32 v67, vcc, 1.0, v64, 1.0
	s_and_b64 s[4:5], exec, s[30:31]
	v_fma_f32 v68, -v65, v66, 1.0
	v_fmac_f32_e32 v66, v68, v66
	v_mul_f32_e32 v68, v67, v66
	v_fma_f32 v69, -v65, v68, v67
	v_fmac_f32_e32 v68, v69, v66
	v_fma_f32 v65, -v65, v68, v67
	v_div_fmas_f32 v65, v65, v66, v68
	v_div_fixup_f32 v64, v65, v64, 1.0
	s_mov_b64 vcc, s[4:5]
	s_cbranch_vccz .LBB0_434
	global_load_dwordx4 v[116:119], v[188:189], off
	global_load_dwordx4 v[120:123], v[188:189], off offset:32
	global_load_dwordx4 v[124:127], v[188:189], off offset:64
	global_load_dwordx4 v[128:131], v[188:189], off offset:96
	global_load_dwordx4 v[132:135], v[188:189], off offset:128
	global_load_dwordx4 v[136:139], v[188:189], off offset:160
	global_load_dwordx4 v[140:143], v[188:189], off offset:192
	global_load_dwordx4 v[144:147], v[188:189], off offset:224
	ds_read2st64_b32 v[68:69], v210 offset0:224 offset1:225
	v_mul_f32_e32 v66, v205, v64
	ds_read2st64_b32 v[70:71], v210 offset0:226 offset1:227
	ds_read2st64_b32 v[72:73], v210 offset0:228 offset1:229
	ds_read2st64_b32 v[74:75], v210 offset0:230 offset1:231
	v_mov_b32_e32 v88, v29
	s_waitcnt lgkmcnt(3)
	v_and_b32_e32 v67, 0xffff0000, v68
	v_lshlrev_b32_e32 v65, 16, v68
	v_fma_f32 v67, -v49, v66, v67
	v_fma_f32 v65, -v48, v66, v65
	v_mul_f32_e32 v67, v67, v67
	v_and_b32_e32 v68, 0xffff0000, v69
	v_fmac_f32_e32 v67, v65, v65
	v_lshlrev_b32_e32 v65, 16, v69
	v_fma_f32 v68, -v51, v66, v68
	v_fma_f32 v65, -v50, v66, v65
	v_mul_f32_e32 v68, v68, v68
	v_fmac_f32_e32 v68, v65, v65
	v_add_f32_e32 v65, v67, v68
	s_waitcnt lgkmcnt(2)
	v_and_b32_e32 v68, 0xffff0000, v70
	v_lshlrev_b32_e32 v67, 16, v70
	v_fma_f32 v68, -v53, v66, v68
	v_fma_f32 v67, -v52, v66, v67
	v_mul_f32_e32 v68, v68, v68
	v_fmac_f32_e32 v68, v67, v67
	v_add_f32_e32 v65, v65, v68
	v_and_b32_e32 v68, 0xffff0000, v71
	v_lshlrev_b32_e32 v67, 16, v71
	v_fma_f32 v68, -v55, v66, v68
	v_fma_f32 v67, -v54, v66, v67
	v_mul_f32_e32 v68, v68, v68
	v_fmac_f32_e32 v68, v67, v67
	v_add_f32_e32 v65, v65, v68
	s_waitcnt lgkmcnt(1)
	v_and_b32_e32 v68, 0xffff0000, v72
	v_lshlrev_b32_e32 v67, 16, v72
	v_fma_f32 v68, -v57, v66, v68
	v_fma_f32 v67, -v56, v66, v67
	v_mul_f32_e32 v68, v68, v68
	v_fmac_f32_e32 v68, v67, v67
	v_add_f32_e32 v65, v65, v68
	v_and_b32_e32 v68, 0xffff0000, v73
	v_lshlrev_b32_e32 v67, 16, v73
	v_fma_f32 v68, -v59, v66, v68
	v_fma_f32 v67, -v58, v66, v67
	v_mul_f32_e32 v68, v68, v68
	v_fmac_f32_e32 v68, v67, v67
	v_add_f32_e32 v65, v65, v68
	s_waitcnt lgkmcnt(0)
	v_and_b32_e32 v68, 0xffff0000, v74
	v_lshlrev_b32_e32 v67, 16, v74
	v_fma_f32 v68, -v61, v66, v68
	v_fma_f32 v67, -v60, v66, v67
	v_mul_f32_e32 v68, v68, v68
	v_fmac_f32_e32 v68, v67, v67
	v_add_f32_e32 v65, v65, v68
	v_and_b32_e32 v68, 0xffff0000, v75
	v_fma_f32 v68, -v63, v66, v68
	v_mul_f32_e32 v70, v68, v68
	ds_read2st64_b32 v[68:69], v210 offset0:232 offset1:233
	v_lshlrev_b32_e32 v67, 16, v75
	v_fma_f32 v67, -v62, v66, v67
	v_fmac_f32_e32 v70, v67, v67
	v_add_f32_e32 v65, v65, v70
	s_waitcnt lgkmcnt(0)
	v_lshlrev_b32_e32 v67, 16, v68
	v_and_b32_e32 v68, 0xffff0000, v68
	v_fma_f32 v68, -v33, v66, v68
	v_fma_f32 v67, -v32, v66, v67
	v_mul_f32_e32 v68, v68, v68
	v_fmac_f32_e32 v68, v67, v67
	v_add_f32_e32 v65, v65, v68
	v_and_b32_e32 v68, 0xffff0000, v69
	ds_read2st64_b32 v[70:71], v210 offset0:234 offset1:235
	ds_read2st64_b32 v[72:73], v210 offset0:236 offset1:237
	ds_read2st64_b32 v[74:75], v210 offset0:238 offset1:239
	v_lshlrev_b32_e32 v67, 16, v69
	v_fma_f32 v68, -v35, v66, v68
	v_fma_f32 v67, -v34, v66, v67
	v_mul_f32_e32 v68, v68, v68
	v_fmac_f32_e32 v68, v67, v67
	v_add_f32_e32 v65, v65, v68
	s_waitcnt lgkmcnt(2)
	v_and_b32_e32 v68, 0xffff0000, v70
	v_lshlrev_b32_e32 v67, 16, v70
	v_fma_f32 v68, -v37, v66, v68
	v_fma_f32 v67, -v36, v66, v67
	v_mul_f32_e32 v68, v68, v68
	v_fmac_f32_e32 v68, v67, v67
	v_add_f32_e32 v65, v65, v68
	v_and_b32_e32 v68, 0xffff0000, v71
	v_lshlrev_b32_e32 v67, 16, v71
	v_fma_f32 v68, -v39, v66, v68
	v_fma_f32 v67, -v38, v66, v67
	v_mul_f32_e32 v68, v68, v68
	v_fmac_f32_e32 v68, v67, v67
	v_add_f32_e32 v65, v65, v68
	s_waitcnt lgkmcnt(1)
	v_and_b32_e32 v68, 0xffff0000, v72
	v_lshlrev_b32_e32 v67, 16, v72
	v_fma_f32 v68, -v41, v66, v68
	v_fma_f32 v67, -v40, v66, v67
	v_mul_f32_e32 v68, v68, v68
	v_fmac_f32_e32 v68, v67, v67
	v_add_f32_e32 v65, v65, v68
	v_and_b32_e32 v68, 0xffff0000, v73
	v_lshlrev_b32_e32 v67, 16, v73
	v_fma_f32 v68, -v43, v66, v68
	v_fma_f32 v67, -v42, v66, v67
	v_mul_f32_e32 v68, v68, v68
	v_fmac_f32_e32 v68, v67, v67
	v_add_f32_e32 v65, v65, v68
	s_waitcnt lgkmcnt(0)
	v_and_b32_e32 v68, 0xffff0000, v74
	v_lshlrev_b32_e32 v67, 16, v74
	v_fma_f32 v68, -v45, v66, v68
	v_fma_f32 v67, -v44, v66, v67
	v_mul_f32_e32 v68, v68, v68
	v_fmac_f32_e32 v68, v67, v67
	v_add_f32_e32 v65, v65, v68
	v_and_b32_e32 v68, 0xffff0000, v75
	v_fma_f32 v68, -v47, v66, v68
	v_mul_f32_e32 v70, v68, v68
	ds_read2st64_b32 v[68:69], v210 offset0:240 offset1:241
	v_lshlrev_b32_e32 v67, 16, v75
	v_fma_f32 v67, -v46, v66, v67
	v_fmac_f32_e32 v70, v67, v67
	v_add_f32_e32 v65, v65, v70
	s_waitcnt lgkmcnt(0)
	v_lshlrev_b32_e32 v67, 16, v68
	v_and_b32_e32 v68, 0xffff0000, v68
	v_fma_f32 v68, -v17, v66, v68
	v_fma_f32 v67, -v16, v66, v67
	v_mul_f32_e32 v68, v68, v68
	v_fmac_f32_e32 v68, v67, v67
	v_add_f32_e32 v65, v65, v68
	v_and_b32_e32 v68, 0xffff0000, v69
	ds_read2st64_b32 v[70:71], v210 offset0:242 offset1:243
	ds_read2st64_b32 v[72:73], v210 offset0:244 offset1:245
	ds_read2st64_b32 v[74:75], v210 offset0:246 offset1:247
	v_lshlrev_b32_e32 v67, 16, v69
	v_fma_f32 v68, -v19, v66, v68
	v_fma_f32 v67, -v18, v66, v67
	v_mul_f32_e32 v68, v68, v68
	v_fmac_f32_e32 v68, v67, v67
	v_add_f32_e32 v65, v65, v68
	s_waitcnt lgkmcnt(2)
	v_and_b32_e32 v68, 0xffff0000, v70
	v_lshlrev_b32_e32 v67, 16, v70
	v_fma_f32 v68, -v21, v66, v68
	v_fma_f32 v67, -v20, v66, v67
	v_mul_f32_e32 v68, v68, v68
	v_fmac_f32_e32 v68, v67, v67
	v_add_f32_e32 v65, v65, v68
	v_and_b32_e32 v68, 0xffff0000, v71
	v_lshlrev_b32_e32 v67, 16, v71
	v_fma_f32 v68, -v23, v66, v68
	v_fma_f32 v67, -v22, v66, v67
	v_mul_f32_e32 v68, v68, v68
	v_fmac_f32_e32 v68, v67, v67
	v_add_f32_e32 v65, v65, v68
	s_waitcnt lgkmcnt(1)
	v_and_b32_e32 v68, 0xffff0000, v72
	v_lshlrev_b32_e32 v67, 16, v72
	v_fma_f32 v68, -v25, v66, v68
	v_fma_f32 v67, -v24, v66, v67
	v_mul_f32_e32 v68, v68, v68
	v_fmac_f32_e32 v68, v67, v67
	v_add_f32_e32 v65, v65, v68
	v_and_b32_e32 v68, 0xffff0000, v73
	v_lshlrev_b32_e32 v67, 16, v73
	v_fma_f32 v68, -v27, v66, v68
	v_fma_f32 v67, -v26, v66, v67
	v_mul_f32_e32 v68, v68, v68
	v_fmac_f32_e32 v68, v67, v67
	s_waitcnt lgkmcnt(0)
	v_and_b32_e32 v71, 0xffff0000, v75
	v_and_b32_e32 v70, 0xffff0000, v74
	v_mov_b32_e32 v89, v31
	v_add_f32_e32 v65, v65, v68
	v_lshlrev_b32_e32 v69, 16, v75
	v_lshlrev_b32_e32 v68, 16, v74
	v_mov_b32_e32 v86, v28
	v_mov_b32_e32 v87, v30
	v_pk_fma_f32 v[70:71], v[88:89], v[66:67], v[70:71] op_sel_hi:[1,0,1] neg_lo:[1,0,0] neg_hi:[1,0,0]
	v_pk_fma_f32 v[68:69], v[86:87], v[66:67], v[68:69] op_sel_hi:[1,0,1] neg_lo:[1,0,0] neg_hi:[1,0,0]
	v_pk_mul_f32 v[70:71], v[70:71], v[70:71]
	v_mov_b32_e32 v80, v1
	v_pk_fma_f32 v[68:69], v[68:69], v[68:69], v[70:71]
	ds_read2st64_b32 v[70:71], v210 offset0:248 offset1:249
	v_add_f32_e32 v65, v65, v68
	v_add_f32_e32 v65, v65, v69
	ds_read2st64_b32 v[68:69], v210 offset0:250 offset1:251
	ds_read2st64_b32 v[72:73], v210 offset0:252 offset1:253
	ds_read2st64_b32 v[76:77], v210 offset0:254 offset1:255
	s_waitcnt vmcnt(0)
	s_nop 1
	v_mov_b32_e32 v90, v116
	v_mov_b32_e32 v91, v117
	v_mov_b32_e32 v92, v118
	v_mov_b32_e32 v93, v119
	s_load_dwordx2 s[4:5], s[0:1], 0x68
	s_waitcnt lgkmcnt(0)
	v_lshlrev_b32_e32 v75, 16, v71
	v_lshlrev_b32_e32 v74, 16, v70
	v_and_b32_e32 v71, 0xffff0000, v71
	v_and_b32_e32 v70, 0xffff0000, v70
	v_mov_b32_e32 v81, v3
	v_mov_b32_e32 v78, v0
	v_mov_b32_e32 v79, v2
	v_pk_fma_f32 v[70:71], v[80:81], v[66:67], v[70:71] op_sel_hi:[1,0,1] neg_lo:[1,0,0] neg_hi:[1,0,0]
	v_pk_fma_f32 v[74:75], v[78:79], v[66:67], v[74:75] op_sel_hi:[1,0,1] neg_lo:[1,0,0] neg_hi:[1,0,0]
	v_pk_mul_f32 v[70:71], v[70:71], v[70:71]
	global_load_dwordx4 v[94:97], v212, s[4:5]
	v_pk_fma_f32 v[70:71], v[74:75], v[74:75], v[70:71]
	v_mov_b32_e32 v84, v5
	v_add_f32_e32 v65, v65, v70
	v_add_f32_e32 v65, v65, v71
	v_lshlrev_b32_e32 v71, 16, v69
	v_lshlrev_b32_e32 v70, 16, v68
	v_and_b32_e32 v69, 0xffff0000, v69
	v_and_b32_e32 v68, 0xffff0000, v68
	v_mov_b32_e32 v85, v7
	v_mov_b32_e32 v82, v4
	v_mov_b32_e32 v83, v6
	v_pk_fma_f32 v[68:69], v[84:85], v[66:67], v[68:69] op_sel_hi:[1,0,1] neg_lo:[1,0,0] neg_hi:[1,0,0]
	v_pk_fma_f32 v[70:71], v[82:83], v[66:67], v[70:71] op_sel_hi:[1,0,1] neg_lo:[1,0,0] neg_hi:[1,0,0]
	v_pk_mul_f32 v[68:69], v[68:69], v[68:69]
	v_and_b32_e32 v75, 0xffff0000, v73
	v_pk_fma_f32 v[68:69], v[70:71], v[70:71], v[68:69]
	v_and_b32_e32 v74, 0xffff0000, v72
	v_add_f32_e32 v65, v65, v68
	v_add_f32_e32 v65, v65, v69
	v_lshlrev_b32_e32 v69, 16, v73
	v_lshlrev_b32_e32 v68, 16, v72
	v_mov_b32_e32 v72, v9
	v_mov_b32_e32 v73, v11
	v_mov_b32_e32 v70, v8
	v_mov_b32_e32 v71, v10
	v_pk_fma_f32 v[74:75], v[72:73], v[66:67], v[74:75] op_sel_hi:[1,0,1] neg_lo:[1,0,0] neg_hi:[1,0,0]
	v_pk_fma_f32 v[68:69], v[70:71], v[66:67], v[68:69] op_sel_hi:[1,0,1] neg_lo:[1,0,0] neg_hi:[1,0,0]
	v_pk_mul_f32 v[74:75], v[74:75], v[74:75]
	v_and_b32_e32 v99, 0xffff0000, v77
	v_pk_fma_f32 v[68:69], v[68:69], v[68:69], v[74:75]
	v_and_b32_e32 v98, 0xffff0000, v76
	v_add_f32_e32 v65, v65, v68
	v_add_f32_e32 v65, v65, v69
	v_lshlrev_b32_e32 v69, 16, v77
	v_lshlrev_b32_e32 v68, 16, v76
	v_mov_b32_e32 v76, v13
	v_mov_b32_e32 v77, v15
	v_mov_b32_e32 v74, v12
	v_mov_b32_e32 v75, v14
	v_pk_fma_f32 v[98:99], v[76:77], v[66:67], v[98:99] op_sel_hi:[1,0,1] neg_lo:[1,0,0] neg_hi:[1,0,0]
	v_pk_fma_f32 v[68:69], v[74:75], v[66:67], v[68:69] op_sel_hi:[1,0,1] neg_lo:[1,0,0] neg_hi:[1,0,0]
	v_pk_mul_f32 v[98:99], v[98:99], v[98:99]
	ds_read2st64_b32 v[102:103], v210 offset0:224 offset1:225
	ds_read2st64_b32 v[104:105], v210 offset0:226 offset1:227
	v_pk_fma_f32 v[68:69], v[68:69], v[68:69], v[98:99]
	global_load_dwordx4 v[98:101], v212, s[4:5] offset:16
	v_add_f32_e32 v65, v65, v68
	v_add_f32_e32 v65, v65, v69
	ds_bpermute_b32 v67, v204, v65
	s_waitcnt lgkmcnt(0)
	v_add_f32_e32 v65, v65, v67
	v_fmamk_f32 v65, v65, 0x3c000000, v211
	v_mul_f32_e32 v67, 0x4b800000, v65
	v_cmp_gt_f32_e32 vcc, s72, v65
	s_waitcnt vmcnt(2)
	v_lshlrev_b32_e32 v110, 16, v90
	v_cndmask_b32_e32 v65, v65, v67, vcc
	v_rsq_f32_e32 v65, v65
	v_and_b32_e32 v111, 0xffff0000, v90
	v_mul_f32_e32 v67, 0x45800000, v65
	v_cndmask_b32_e32 v65, v65, v67, vcc
	v_mul_f32_e32 v68, 0x3f4ccccd, v65
	v_lshlrev_b32_e32 v65, 16, v102
	v_fma_f32 v106, -v48, v66, v65
	v_and_b32_e32 v65, 0xffff0000, v102
	v_fma_f32 v107, -v49, v66, v65
	v_lshlrev_b32_e32 v65, 16, v104
	v_fma_f32 v108, -v52, v66, v65
	v_and_b32_e32 v65, 0xffff0000, v104
	v_fma_f32 v109, -v53, v66, v65
	v_lshlrev_b32_e32 v65, 16, v103
	v_fma_f32 v102, -v50, v66, v65
	v_and_b32_e32 v65, 0xffff0000, v103
	v_fma_f32 v103, -v51, v66, v65
	v_lshlrev_b32_e32 v65, 16, v105
	v_fma_f32 v104, -v54, v66, v65
	v_and_b32_e32 v65, 0xffff0000, v105
	v_fma_f32 v105, -v55, v66, v65
	v_mul_f32_e32 v65, 0xbfb8aa3b, v110
	v_exp_f32_e32 v65, v65
	v_mul_f32_e32 v67, 0xbfb8aa3b, v111
	v_exp_f32_e32 v67, v67
	v_permlane32_swap_b32_e32 v106, v108
	v_add_f32_e32 v65, 1.0, v65
	v_rcp_f32_e32 v112, v65
	v_add_f32_e32 v65, 1.0, v67
	v_rcp_f32_e32 v113, v65
	v_permlane32_swap_b32_e32 v107, v109
	v_pk_mul_f32 v[106:107], v[68:69], v[106:107] op_sel_hi:[0,1]
	s_waitcnt vmcnt(1)
	v_pk_mul_f32 v[94:95], v[94:95], v[106:107]
	v_pk_mul_f32 v[106:107], v[112:113], v[110:111]
	v_lshlrev_b32_e32 v110, 16, v91
	v_and_b32_e32 v111, 0xffff0000, v91
	v_mul_f32_e32 v65, 0xbfb8aa3b, v110
	v_exp_f32_e32 v65, v65
	v_mul_f32_e32 v67, 0xbfb8aa3b, v111
	v_exp_f32_e32 v67, v67
	v_permlane32_swap_b32_e32 v102, v104
	v_permlane32_swap_b32_e32 v103, v105
	v_add_f32_e32 v65, 1.0, v65
	v_pk_mul_f32 v[90:91], v[94:95], v[106:107]
	v_rcp_f32_e32 v94, v65
	v_add_f32_e32 v65, 1.0, v67
	v_pk_mul_f32 v[102:103], v[68:69], v[102:103] op_sel_hi:[0,1]
	v_rcp_f32_e32 v95, v65
	v_pk_mul_f32 v[96:97], v[96:97], v[102:103]
	v_lshlrev_b32_e32 v102, 16, v92
	v_and_b32_e32 v103, 0xffff0000, v92
	v_mul_f32_e32 v65, 0xbfb8aa3b, v102
	v_exp_f32_e32 v65, v65
	v_mul_f32_e32 v67, 0xbfb8aa3b, v103
	v_exp_f32_e32 v67, v67
	v_pk_mul_f32 v[94:95], v[94:95], v[110:111]
	v_cvt_pk_bf16_f32 v90, v90, v91
	v_pk_mul_f32 v[94:95], v[96:97], v[94:95]
	v_add_f32_e32 v65, 1.0, v65
	v_cvt_pk_bf16_f32 v91, v94, v95
	v_pk_mul_f32 v[94:95], v[68:69], v[108:109] op_sel_hi:[0,1]
	v_rcp_f32_e32 v96, v65
	v_add_f32_e32 v65, 1.0, v67
	s_waitcnt vmcnt(0)
	v_pk_mul_f32 v[94:95], v[98:99], v[94:95]
	v_lshlrev_b32_e32 v98, 16, v93
	v_rcp_f32_e32 v97, v65
	v_and_b32_e32 v99, 0xffff0000, v93
	v_mul_f32_e32 v65, 0xbfb8aa3b, v98
	v_exp_f32_e32 v65, v65
	v_mul_f32_e32 v67, 0xbfb8aa3b, v99
	v_exp_f32_e32 v67, v67
	v_pk_mul_f32 v[96:97], v[96:97], v[102:103]
	v_add_f32_e32 v65, 1.0, v65
	v_pk_mul_f32 v[92:93], v[94:95], v[96:97]
	v_rcp_f32_e32 v94, v65
	v_add_f32_e32 v65, 1.0, v67
	v_rcp_f32_e32 v95, v65
	v_pk_mul_f32 v[96:97], v[68:69], v[104:105] op_sel_hi:[0,1]
	v_pk_mul_f32 v[96:97], v[100:101], v[96:97]
	v_cvt_pk_bf16_f32 v92, v92, v93
	v_pk_mul_f32 v[94:95], v[94:95], v[98:99]
	s_nop 0
	v_pk_mul_f32 v[94:95], v[96:97], v[94:95]
	s_nop 0
	v_cvt_pk_bf16_f32 v93, v94, v95
	global_store_dwordx4 v[186:187], v[90:93], off
	s_nop 1
	v_mov_b32_e32 v90, v120
	v_mov_b32_e32 v91, v121
	v_mov_b32_e32 v92, v122
	v_mov_b32_e32 v93, v123
	global_load_dwordx4 v[94:97], v212, s[4:5] offset:64
	global_load_dwordx4 v[98:101], v212, s[4:5] offset:80
	ds_read2st64_b32 v[102:103], v210 offset0:228 offset1:229
	ds_read2st64_b32 v[104:105], v210 offset0:230 offset1:231
	s_waitcnt lgkmcnt(1)
	v_lshlrev_b32_e32 v65, 16, v102
	v_fma_f32 v106, -v56, v66, v65
	v_and_b32_e32 v65, 0xffff0000, v102
	v_fma_f32 v107, -v57, v66, v65
	s_waitcnt lgkmcnt(0)
	v_lshlrev_b32_e32 v65, 16, v104
	v_fma_f32 v108, -v60, v66, v65
	v_and_b32_e32 v65, 0xffff0000, v104
	v_fma_f32 v109, -v61, v66, v65
	v_lshlrev_b32_e32 v65, 16, v103
	v_fma_f32 v102, -v58, v66, v65
	v_and_b32_e32 v65, 0xffff0000, v103
	v_fma_f32 v103, -v59, v66, v65
	v_lshlrev_b32_e32 v65, 16, v105
	v_fma_f32 v104, -v62, v66, v65
	v_and_b32_e32 v65, 0xffff0000, v105
	v_fma_f32 v105, -v63, v66, v65
	v_permlane32_swap_b32_e32 v106, v108
	v_permlane32_swap_b32_e32 v107, v109
	v_pk_mul_f32 v[106:107], v[68:69], v[106:107] op_sel_hi:[0,1]
	v_permlane32_swap_b32_e32 v102, v104
	v_permlane32_swap_b32_e32 v103, v105
	v_pk_mul_f32 v[102:103], v[68:69], v[102:103] op_sel_hi:[0,1]
	s_waitcnt vmcnt(2)
	v_lshlrev_b32_e32 v110, 16, v90
	v_and_b32_e32 v111, 0xffff0000, v90
	v_mul_f32_e32 v65, 0xbfb8aa3b, v110
	v_exp_f32_e32 v65, v65
	v_mul_f32_e32 v67, 0xbfb8aa3b, v111
	v_exp_f32_e32 v67, v67
	s_waitcnt vmcnt(1)
	v_pk_mul_f32 v[94:95], v[106:107], v[94:95]
	v_add_f32_e32 v65, 1.0, v65
	v_rcp_f32_e32 v112, v65
	v_add_f32_e32 v65, 1.0, v67
	v_rcp_f32_e32 v113, v65
	v_pk_mul_f32 v[96:97], v[96:97], v[102:103]
	v_lshlrev_b32_e32 v102, 16, v92
	v_and_b32_e32 v103, 0xffff0000, v92
	v_pk_mul_f32 v[106:107], v[112:113], v[110:111]
	v_lshlrev_b32_e32 v110, 16, v91
	v_and_b32_e32 v111, 0xffff0000, v91
	v_mul_f32_e32 v65, 0xbfb8aa3b, v110
	v_exp_f32_e32 v65, v65
	v_mul_f32_e32 v67, 0xbfb8aa3b, v111
	v_exp_f32_e32 v67, v67
	v_pk_mul_f32 v[90:91], v[94:95], v[106:107]
	v_add_f32_e32 v65, 1.0, v65
	v_rcp_f32_e32 v94, v65
	v_add_f32_e32 v65, 1.0, v67
	v_rcp_f32_e32 v95, v65
	v_mul_f32_e32 v65, 0xbfb8aa3b, v102
	v_exp_f32_e32 v65, v65
	v_mul_f32_e32 v67, 0xbfb8aa3b, v103
	v_exp_f32_e32 v67, v67
	v_pk_mul_f32 v[94:95], v[94:95], v[110:111]
	v_cvt_pk_bf16_f32 v90, v90, v91
	v_pk_mul_f32 v[94:95], v[96:97], v[94:95]
	v_add_f32_e32 v65, 1.0, v65
	v_cvt_pk_bf16_f32 v91, v94, v95
	v_pk_mul_f32 v[94:95], v[68:69], v[108:109] op_sel_hi:[0,1]
	v_rcp_f32_e32 v96, v65
	v_add_f32_e32 v65, 1.0, v67
	s_waitcnt vmcnt(0)
	v_pk_mul_f32 v[94:95], v[94:95], v[98:99]
	v_lshlrev_b32_e32 v98, 16, v93
	v_rcp_f32_e32 v97, v65
	v_and_b32_e32 v99, 0xffff0000, v93
	v_mul_f32_e32 v65, 0xbfb8aa3b, v98
	v_exp_f32_e32 v65, v65
	v_mul_f32_e32 v67, 0xbfb8aa3b, v99
	v_exp_f32_e32 v67, v67
	v_pk_mul_f32 v[96:97], v[96:97], v[102:103]
	v_add_f32_e32 v65, 1.0, v65
	v_pk_mul_f32 v[92:93], v[94:95], v[96:97]
	v_rcp_f32_e32 v94, v65
	v_add_f32_e32 v65, 1.0, v67
	v_rcp_f32_e32 v95, v65
	v_pk_mul_f32 v[96:97], v[68:69], v[104:105] op_sel_hi:[0,1]
	v_pk_mul_f32 v[96:97], v[96:97], v[100:101]
	v_cvt_pk_bf16_f32 v92, v92, v93
	v_pk_mul_f32 v[94:95], v[94:95], v[98:99]
	s_nop 0
	v_pk_mul_f32 v[94:95], v[96:97], v[94:95]
	s_nop 0
	v_cvt_pk_bf16_f32 v93, v94, v95
	global_store_dwordx4 v[186:187], v[90:93], off offset:32
	s_nop 1
	v_mov_b32_e32 v90, v124
	v_mov_b32_e32 v91, v125
	v_mov_b32_e32 v92, v126
	v_mov_b32_e32 v93, v127
	global_load_dwordx4 v[94:97], v212, s[4:5] offset:128
	global_load_dwordx4 v[98:101], v212, s[4:5] offset:144
	ds_read2st64_b32 v[102:103], v210 offset0:232 offset1:233
	ds_read2st64_b32 v[104:105], v210 offset0:234 offset1:235
	s_waitcnt lgkmcnt(1)
	v_lshlrev_b32_e32 v65, 16, v102
	v_fma_f32 v106, -v32, v66, v65
	v_and_b32_e32 v65, 0xffff0000, v102
	v_fma_f32 v107, -v33, v66, v65
	s_waitcnt lgkmcnt(0)
	v_lshlrev_b32_e32 v65, 16, v104
	v_fma_f32 v108, -v36, v66, v65
	v_and_b32_e32 v65, 0xffff0000, v104
	v_fma_f32 v109, -v37, v66, v65
	v_lshlrev_b32_e32 v65, 16, v103
	v_fma_f32 v102, -v34, v66, v65
	v_and_b32_e32 v65, 0xffff0000, v103
	v_fma_f32 v103, -v35, v66, v65
	v_lshlrev_b32_e32 v65, 16, v105
	v_fma_f32 v104, -v38, v66, v65
	v_and_b32_e32 v65, 0xffff0000, v105
	v_fma_f32 v105, -v39, v66, v65
	v_permlane32_swap_b32_e32 v106, v108
	v_permlane32_swap_b32_e32 v107, v109
	v_pk_mul_f32 v[106:107], v[68:69], v[106:107] op_sel_hi:[0,1]
	v_permlane32_swap_b32_e32 v102, v104
	v_permlane32_swap_b32_e32 v103, v105
	v_pk_mul_f32 v[102:103], v[68:69], v[102:103] op_sel_hi:[0,1]
	s_waitcnt vmcnt(2)
	v_lshlrev_b32_e32 v110, 16, v90
	v_and_b32_e32 v111, 0xffff0000, v90
	v_mul_f32_e32 v65, 0xbfb8aa3b, v110
	v_exp_f32_e32 v65, v65
	v_mul_f32_e32 v67, 0xbfb8aa3b, v111
	v_exp_f32_e32 v67, v67
	s_waitcnt vmcnt(1)
	v_pk_mul_f32 v[94:95], v[106:107], v[94:95]
	v_add_f32_e32 v65, 1.0, v65
	v_rcp_f32_e32 v112, v65
	v_add_f32_e32 v65, 1.0, v67
	v_rcp_f32_e32 v113, v65
	v_pk_mul_f32 v[96:97], v[96:97], v[102:103]
	v_lshlrev_b32_e32 v102, 16, v92
	v_and_b32_e32 v103, 0xffff0000, v92
	v_pk_mul_f32 v[106:107], v[112:113], v[110:111]
	v_lshlrev_b32_e32 v110, 16, v91
	v_and_b32_e32 v111, 0xffff0000, v91
	v_mul_f32_e32 v65, 0xbfb8aa3b, v110
	v_exp_f32_e32 v65, v65
	v_mul_f32_e32 v67, 0xbfb8aa3b, v111
	v_exp_f32_e32 v67, v67
	v_pk_mul_f32 v[90:91], v[94:95], v[106:107]
	v_add_f32_e32 v65, 1.0, v65
	v_rcp_f32_e32 v94, v65
	v_add_f32_e32 v65, 1.0, v67
	v_rcp_f32_e32 v95, v65
	v_mul_f32_e32 v65, 0xbfb8aa3b, v102
	v_exp_f32_e32 v65, v65
	v_mul_f32_e32 v67, 0xbfb8aa3b, v103
	v_exp_f32_e32 v67, v67
	v_pk_mul_f32 v[94:95], v[94:95], v[110:111]
	v_cvt_pk_bf16_f32 v90, v90, v91
	v_pk_mul_f32 v[94:95], v[96:97], v[94:95]
	v_add_f32_e32 v65, 1.0, v65
	v_cvt_pk_bf16_f32 v91, v94, v95
	v_pk_mul_f32 v[94:95], v[68:69], v[108:109] op_sel_hi:[0,1]
	v_rcp_f32_e32 v96, v65
	v_add_f32_e32 v65, 1.0, v67
	s_waitcnt vmcnt(0)
	v_pk_mul_f32 v[94:95], v[94:95], v[98:99]
	v_lshlrev_b32_e32 v98, 16, v93
	v_rcp_f32_e32 v97, v65
	v_and_b32_e32 v99, 0xffff0000, v93
	v_mul_f32_e32 v65, 0xbfb8aa3b, v98
	v_exp_f32_e32 v65, v65
	v_mul_f32_e32 v67, 0xbfb8aa3b, v99
	v_exp_f32_e32 v67, v67
	v_pk_mul_f32 v[96:97], v[96:97], v[102:103]
	v_add_f32_e32 v65, 1.0, v65
	v_pk_mul_f32 v[92:93], v[94:95], v[96:97]
	v_rcp_f32_e32 v94, v65
	v_add_f32_e32 v65, 1.0, v67
	v_rcp_f32_e32 v95, v65
	v_pk_mul_f32 v[96:97], v[68:69], v[104:105] op_sel_hi:[0,1]
	v_pk_mul_f32 v[96:97], v[96:97], v[100:101]
	v_cvt_pk_bf16_f32 v92, v92, v93
	v_pk_mul_f32 v[94:95], v[94:95], v[98:99]
	s_nop 0
	v_pk_mul_f32 v[94:95], v[96:97], v[94:95]
	s_nop 0
	v_cvt_pk_bf16_f32 v93, v94, v95
	global_store_dwordx4 v[186:187], v[90:93], off offset:64
	s_nop 1
	v_mov_b32_e32 v90, v128
	v_mov_b32_e32 v91, v129
	v_mov_b32_e32 v92, v130
	v_mov_b32_e32 v93, v131
	global_load_dwordx4 v[94:97], v212, s[4:5] offset:192
	global_load_dwordx4 v[98:101], v212, s[4:5] offset:208
	ds_read2st64_b32 v[102:103], v210 offset0:236 offset1:237
	ds_read2st64_b32 v[104:105], v210 offset0:238 offset1:239
	s_waitcnt lgkmcnt(1)
	v_lshlrev_b32_e32 v65, 16, v102
	v_fma_f32 v106, -v40, v66, v65
	v_and_b32_e32 v65, 0xffff0000, v102
	v_fma_f32 v107, -v41, v66, v65
	s_waitcnt lgkmcnt(0)
	v_lshlrev_b32_e32 v65, 16, v104
	v_fma_f32 v108, -v44, v66, v65
	v_and_b32_e32 v65, 0xffff0000, v104
	v_fma_f32 v109, -v45, v66, v65
	v_lshlrev_b32_e32 v65, 16, v103
	v_fma_f32 v102, -v42, v66, v65
	v_and_b32_e32 v65, 0xffff0000, v103
	v_fma_f32 v103, -v43, v66, v65
	v_lshlrev_b32_e32 v65, 16, v105
	v_fma_f32 v104, -v46, v66, v65
	v_and_b32_e32 v65, 0xffff0000, v105
	v_fma_f32 v105, -v47, v66, v65
	v_permlane32_swap_b32_e32 v106, v108
	v_permlane32_swap_b32_e32 v107, v109
	v_pk_mul_f32 v[106:107], v[68:69], v[106:107] op_sel_hi:[0,1]
	v_permlane32_swap_b32_e32 v102, v104
	v_permlane32_swap_b32_e32 v103, v105
	v_pk_mul_f32 v[102:103], v[68:69], v[102:103] op_sel_hi:[0,1]
	s_waitcnt vmcnt(2)
	v_lshlrev_b32_e32 v110, 16, v90
	v_and_b32_e32 v111, 0xffff0000, v90
	v_mul_f32_e32 v65, 0xbfb8aa3b, v110
	v_exp_f32_e32 v65, v65
	v_mul_f32_e32 v67, 0xbfb8aa3b, v111
	v_exp_f32_e32 v67, v67
	s_waitcnt vmcnt(1)
	v_pk_mul_f32 v[94:95], v[106:107], v[94:95]
	v_add_f32_e32 v65, 1.0, v65
	v_rcp_f32_e32 v112, v65
	v_add_f32_e32 v65, 1.0, v67
	v_rcp_f32_e32 v113, v65
	v_pk_mul_f32 v[96:97], v[96:97], v[102:103]
	v_lshlrev_b32_e32 v102, 16, v92
	v_and_b32_e32 v103, 0xffff0000, v92
	v_pk_mul_f32 v[106:107], v[112:113], v[110:111]
	v_lshlrev_b32_e32 v110, 16, v91
	v_and_b32_e32 v111, 0xffff0000, v91
	v_mul_f32_e32 v65, 0xbfb8aa3b, v110
	v_exp_f32_e32 v65, v65
	v_mul_f32_e32 v67, 0xbfb8aa3b, v111
	v_exp_f32_e32 v67, v67
	v_pk_mul_f32 v[90:91], v[94:95], v[106:107]
	v_add_f32_e32 v65, 1.0, v65
	v_rcp_f32_e32 v94, v65
	v_add_f32_e32 v65, 1.0, v67
	v_rcp_f32_e32 v95, v65
	v_mul_f32_e32 v65, 0xbfb8aa3b, v102
	v_exp_f32_e32 v65, v65
	v_mul_f32_e32 v67, 0xbfb8aa3b, v103
	v_exp_f32_e32 v67, v67
	v_pk_mul_f32 v[94:95], v[94:95], v[110:111]
	v_cvt_pk_bf16_f32 v90, v90, v91
	v_pk_mul_f32 v[94:95], v[96:97], v[94:95]
	v_add_f32_e32 v65, 1.0, v65
	v_cvt_pk_bf16_f32 v91, v94, v95
	v_pk_mul_f32 v[94:95], v[68:69], v[108:109] op_sel_hi:[0,1]
	v_rcp_f32_e32 v96, v65
	v_add_f32_e32 v65, 1.0, v67
	s_waitcnt vmcnt(0)
	v_pk_mul_f32 v[94:95], v[94:95], v[98:99]
	v_lshlrev_b32_e32 v98, 16, v93
	v_rcp_f32_e32 v97, v65
	v_and_b32_e32 v99, 0xffff0000, v93
	v_mul_f32_e32 v65, 0xbfb8aa3b, v98
	v_exp_f32_e32 v65, v65
	v_mul_f32_e32 v67, 0xbfb8aa3b, v99
	v_exp_f32_e32 v67, v67
	v_pk_mul_f32 v[96:97], v[96:97], v[102:103]
	v_add_f32_e32 v65, 1.0, v65
	v_pk_mul_f32 v[92:93], v[94:95], v[96:97]
	v_rcp_f32_e32 v94, v65
	v_add_f32_e32 v65, 1.0, v67
	v_rcp_f32_e32 v95, v65
	v_pk_mul_f32 v[96:97], v[68:69], v[104:105] op_sel_hi:[0,1]
	v_pk_mul_f32 v[96:97], v[96:97], v[100:101]
	v_cvt_pk_bf16_f32 v92, v92, v93
	v_pk_mul_f32 v[94:95], v[94:95], v[98:99]
	s_nop 0
	v_pk_mul_f32 v[94:95], v[96:97], v[94:95]
	s_nop 0
	v_cvt_pk_bf16_f32 v93, v94, v95
	global_store_dwordx4 v[186:187], v[90:93], off offset:96
	s_nop 1
	v_mov_b32_e32 v90, v132
	v_mov_b32_e32 v91, v133
	v_mov_b32_e32 v92, v134
	v_mov_b32_e32 v93, v135
	global_load_dwordx4 v[94:97], v212, s[4:5] offset:256
	global_load_dwordx4 v[98:101], v212, s[4:5] offset:272
	ds_read2st64_b32 v[102:103], v210 offset0:240 offset1:241
	ds_read2st64_b32 v[104:105], v210 offset0:242 offset1:243
	s_waitcnt lgkmcnt(1)
	v_lshlrev_b32_e32 v65, 16, v102
	v_fma_f32 v106, -v16, v66, v65
	v_and_b32_e32 v65, 0xffff0000, v102
	v_fma_f32 v107, -v17, v66, v65
	s_waitcnt lgkmcnt(0)
	v_lshlrev_b32_e32 v65, 16, v104
	v_fma_f32 v108, -v20, v66, v65
	v_and_b32_e32 v65, 0xffff0000, v104
	v_fma_f32 v109, -v21, v66, v65
	v_lshlrev_b32_e32 v65, 16, v103
	v_fma_f32 v102, -v18, v66, v65
	v_and_b32_e32 v65, 0xffff0000, v103
	v_fma_f32 v103, -v19, v66, v65
	v_lshlrev_b32_e32 v65, 16, v105
	v_fma_f32 v104, -v22, v66, v65
	v_and_b32_e32 v65, 0xffff0000, v105
	v_fma_f32 v105, -v23, v66, v65
	v_permlane32_swap_b32_e32 v106, v108
	v_permlane32_swap_b32_e32 v107, v109
	v_pk_mul_f32 v[106:107], v[68:69], v[106:107] op_sel_hi:[0,1]
	v_permlane32_swap_b32_e32 v102, v104
	v_permlane32_swap_b32_e32 v103, v105
	v_pk_mul_f32 v[102:103], v[68:69], v[102:103] op_sel_hi:[0,1]
	s_waitcnt vmcnt(2)
	v_lshlrev_b32_e32 v110, 16, v90
	v_and_b32_e32 v111, 0xffff0000, v90
	v_mul_f32_e32 v65, 0xbfb8aa3b, v110
	v_exp_f32_e32 v65, v65
	v_mul_f32_e32 v67, 0xbfb8aa3b, v111
	v_exp_f32_e32 v67, v67
	s_waitcnt vmcnt(1)
	v_pk_mul_f32 v[94:95], v[106:107], v[94:95]
	v_add_f32_e32 v65, 1.0, v65
	v_rcp_f32_e32 v112, v65
	v_add_f32_e32 v65, 1.0, v67
	v_rcp_f32_e32 v113, v65
	v_pk_mul_f32 v[96:97], v[96:97], v[102:103]
	v_lshlrev_b32_e32 v102, 16, v92
	v_and_b32_e32 v103, 0xffff0000, v92
	v_pk_mul_f32 v[106:107], v[112:113], v[110:111]
	v_lshlrev_b32_e32 v110, 16, v91
	v_and_b32_e32 v111, 0xffff0000, v91
	v_mul_f32_e32 v65, 0xbfb8aa3b, v110
	v_exp_f32_e32 v65, v65
	v_mul_f32_e32 v67, 0xbfb8aa3b, v111
	v_exp_f32_e32 v67, v67
	v_pk_mul_f32 v[90:91], v[94:95], v[106:107]
	v_add_f32_e32 v65, 1.0, v65
	v_rcp_f32_e32 v94, v65
	v_add_f32_e32 v65, 1.0, v67
	v_rcp_f32_e32 v95, v65
	v_mul_f32_e32 v65, 0xbfb8aa3b, v102
	v_exp_f32_e32 v65, v65
	v_mul_f32_e32 v67, 0xbfb8aa3b, v103
	v_exp_f32_e32 v67, v67
	v_pk_mul_f32 v[94:95], v[94:95], v[110:111]
	v_cvt_pk_bf16_f32 v90, v90, v91
	v_pk_mul_f32 v[94:95], v[96:97], v[94:95]
	v_add_f32_e32 v65, 1.0, v65
	v_cvt_pk_bf16_f32 v91, v94, v95
	v_pk_mul_f32 v[94:95], v[68:69], v[108:109] op_sel_hi:[0,1]
	v_rcp_f32_e32 v96, v65
	v_add_f32_e32 v65, 1.0, v67
	s_waitcnt vmcnt(0)
	v_pk_mul_f32 v[94:95], v[94:95], v[98:99]
	v_lshlrev_b32_e32 v98, 16, v93
	v_rcp_f32_e32 v97, v65
	v_and_b32_e32 v99, 0xffff0000, v93
	v_mul_f32_e32 v65, 0xbfb8aa3b, v98
	v_exp_f32_e32 v65, v65
	v_mul_f32_e32 v67, 0xbfb8aa3b, v99
	v_exp_f32_e32 v67, v67
	v_pk_mul_f32 v[96:97], v[96:97], v[102:103]
	v_add_f32_e32 v65, 1.0, v65
	v_pk_mul_f32 v[92:93], v[94:95], v[96:97]
	v_rcp_f32_e32 v94, v65
	v_add_f32_e32 v65, 1.0, v67
	v_rcp_f32_e32 v95, v65
	v_pk_mul_f32 v[96:97], v[68:69], v[104:105] op_sel_hi:[0,1]
	v_pk_mul_f32 v[96:97], v[96:97], v[100:101]
	v_cvt_pk_bf16_f32 v92, v92, v93
	v_pk_mul_f32 v[94:95], v[94:95], v[98:99]
	v_pk_mul_f32 v[86:87], v[86:87], v[66:67] op_sel_hi:[1,0]
	v_pk_mul_f32 v[94:95], v[96:97], v[94:95]
	v_pk_mul_f32 v[88:89], v[88:89], v[66:67] op_sel_hi:[1,0]
	v_cvt_pk_bf16_f32 v93, v94, v95
	global_store_dwordx4 v[186:187], v[90:93], off offset:128
	s_nop 1
	v_mov_b32_e32 v90, v136
	v_mov_b32_e32 v91, v137
	v_mov_b32_e32 v92, v138
	v_mov_b32_e32 v93, v139
	global_load_dwordx4 v[94:97], v212, s[4:5] offset:320
	global_load_dwordx4 v[98:101], v212, s[4:5] offset:336
	ds_read2st64_b32 v[102:103], v210 offset0:244 offset1:245
	ds_read2st64_b32 v[104:105], v210 offset0:246 offset1:247
	s_waitcnt lgkmcnt(1)
	v_lshlrev_b32_e32 v65, 16, v102
	v_fma_f32 v106, -v24, v66, v65
	v_and_b32_e32 v65, 0xffff0000, v102
	v_fma_f32 v107, -v25, v66, v65
	s_waitcnt lgkmcnt(0)
	v_lshlrev_b32_e32 v65, 16, v104
	v_sub_f32_e32 v108, v65, v86
	v_and_b32_e32 v65, 0xffff0000, v104
	v_sub_f32_e32 v109, v65, v88
	v_lshlrev_b32_e32 v65, 16, v103
	v_fma_f32 v102, -v26, v66, v65
	v_and_b32_e32 v65, 0xffff0000, v103
	v_fma_f32 v103, -v27, v66, v65
	v_lshlrev_b32_e32 v65, 16, v105
	v_sub_f32_e32 v104, v65, v87
	v_and_b32_e32 v65, 0xffff0000, v105
	v_sub_f32_e32 v105, v65, v89
	v_permlane32_swap_b32_e32 v106, v108
	v_permlane32_swap_b32_e32 v107, v109
	v_pk_mul_f32 v[106:107], v[68:69], v[106:107] op_sel_hi:[0,1]
	v_permlane32_swap_b32_e32 v102, v104
	v_permlane32_swap_b32_e32 v103, v105
	s_waitcnt vmcnt(2)
	v_lshlrev_b32_e32 v86, 16, v90
	v_and_b32_e32 v87, 0xffff0000, v90
	v_mul_f32_e32 v65, 0xbfb8aa3b, v86
	v_exp_f32_e32 v65, v65
	v_mul_f32_e32 v67, 0xbfb8aa3b, v87
	v_exp_f32_e32 v67, v67
	s_waitcnt vmcnt(1)
	v_pk_mul_f32 v[94:95], v[106:107], v[94:95]
	v_add_f32_e32 v65, 1.0, v65
	v_rcp_f32_e32 v88, v65
	v_add_f32_e32 v65, 1.0, v67
	v_rcp_f32_e32 v89, v65
	s_nop 0
	v_pk_mul_f32 v[86:87], v[88:89], v[86:87]
	v_lshlrev_b32_e32 v88, 16, v91
	v_and_b32_e32 v89, 0xffff0000, v91
	v_mul_f32_e32 v65, 0xbfb8aa3b, v88
	v_exp_f32_e32 v65, v65
	v_mul_f32_e32 v67, 0xbfb8aa3b, v89
	v_exp_f32_e32 v67, v67
	v_pk_mul_f32 v[86:87], v[94:95], v[86:87]
	v_add_f32_e32 v65, 1.0, v65
	v_rcp_f32_e32 v90, v65
	v_add_f32_e32 v65, 1.0, v67
	v_rcp_f32_e32 v91, v65
	v_pk_mul_f32 v[94:95], v[68:69], v[102:103] op_sel_hi:[0,1]
	v_pk_mul_f32 v[94:95], v[96:97], v[94:95]
	v_cvt_pk_bf16_f32 v86, v86, v87
	v_pk_mul_f32 v[88:89], v[90:91], v[88:89]
	v_lshlrev_b32_e32 v90, 16, v92
	v_and_b32_e32 v91, 0xffff0000, v92
	v_mul_f32_e32 v65, 0xbfb8aa3b, v90
	v_exp_f32_e32 v65, v65
	v_mul_f32_e32 v67, 0xbfb8aa3b, v91
	v_exp_f32_e32 v67, v67
	v_pk_mul_f32 v[88:89], v[94:95], v[88:89]
	v_add_f32_e32 v65, 1.0, v65
	v_rcp_f32_e32 v94, v65
	v_add_f32_e32 v65, 1.0, v67
	v_lshlrev_b32_e32 v92, 16, v93
	v_rcp_f32_e32 v95, v65
	v_and_b32_e32 v93, 0xffff0000, v93
	v_mul_f32_e32 v65, 0xbfb8aa3b, v92
	v_exp_f32_e32 v65, v65
	v_mul_f32_e32 v67, 0xbfb8aa3b, v93
	v_exp_f32_e32 v67, v67
	v_cvt_pk_bf16_f32 v87, v88, v89
	v_pk_mul_f32 v[88:89], v[68:69], v[108:109] op_sel_hi:[0,1]
	s_waitcnt vmcnt(0)
	v_pk_mul_f32 v[88:89], v[88:89], v[98:99]
	v_pk_mul_f32 v[90:91], v[94:95], v[90:91]
	v_add_f32_e32 v65, 1.0, v65
	v_pk_mul_f32 v[88:89], v[88:89], v[90:91]
	v_rcp_f32_e32 v90, v65
	v_add_f32_e32 v65, 1.0, v67
	v_rcp_f32_e32 v91, v65
	v_pk_mul_f32 v[94:95], v[68:69], v[104:105] op_sel_hi:[0,1]
	v_pk_mul_f32 v[94:95], v[94:95], v[100:101]
	v_cvt_pk_bf16_f32 v88, v88, v89
	v_pk_mul_f32 v[90:91], v[90:91], v[92:93]
	v_pk_mul_f32 v[78:79], v[78:79], v[66:67] op_sel_hi:[1,0]
	v_pk_mul_f32 v[90:91], v[94:95], v[90:91]
	v_pk_mul_f32 v[80:81], v[80:81], v[66:67] op_sel_hi:[1,0]
	v_cvt_pk_bf16_f32 v89, v90, v91
	global_store_dwordx4 v[186:187], v[86:89], off offset:160
	s_nop 1
	v_mov_b32_e32 v86, v140
	v_mov_b32_e32 v87, v141
	v_mov_b32_e32 v88, v142
	v_mov_b32_e32 v89, v143
	global_load_dwordx4 v[90:93], v212, s[4:5] offset:384
	global_load_dwordx4 v[94:97], v212, s[4:5] offset:400
	ds_read2st64_b32 v[98:99], v210 offset0:248 offset1:249
	ds_read2st64_b32 v[100:101], v210 offset0:250 offset1:251
	v_pk_mul_f32 v[82:83], v[82:83], v[66:67] op_sel_hi:[1,0]
	v_pk_mul_f32 v[84:85], v[84:85], v[66:67] op_sel_hi:[1,0]
	s_waitcnt lgkmcnt(1)
	v_lshlrev_b32_e32 v65, 16, v98
	v_sub_f32_e32 v102, v65, v78
	v_and_b32_e32 v65, 0xffff0000, v98
	v_sub_f32_e32 v103, v65, v80
	s_waitcnt lgkmcnt(0)
	v_lshlrev_b32_e32 v65, 16, v100
	v_sub_f32_e32 v104, v65, v82
	v_and_b32_e32 v65, 0xffff0000, v100
	v_sub_f32_e32 v105, v65, v84
	v_lshlrev_b32_e32 v65, 16, v99
	v_sub_f32_e32 v80, v65, v79
	v_and_b32_e32 v65, 0xffff0000, v99
	v_sub_f32_e32 v81, v65, v81
	v_lshlrev_b32_e32 v65, 16, v101
	v_sub_f32_e32 v82, v65, v83
	v_and_b32_e32 v65, 0xffff0000, v101
	v_sub_f32_e32 v83, v65, v85
	v_permlane32_swap_b32_e32 v80, v82
	s_nop 0
	v_permlane32_swap_b32_e32 v81, v83
	v_pk_mul_f32 v[80:81], v[68:69], v[80:81] op_sel_hi:[0,1]
	v_permlane32_swap_b32_e32 v102, v104
	v_permlane32_swap_b32_e32 v103, v105
	v_pk_mul_f32 v[98:99], v[68:69], v[102:103] op_sel_hi:[0,1]
	v_pk_mul_f32 v[82:83], v[68:69], v[82:83] op_sel_hi:[0,1]
	s_waitcnt vmcnt(2)
	v_lshlrev_b32_e32 v78, 16, v86
	v_and_b32_e32 v79, 0xffff0000, v86
	v_mul_f32_e32 v65, 0xbfb8aa3b, v78
	v_exp_f32_e32 v65, v65
	v_mul_f32_e32 v67, 0xbfb8aa3b, v79
	v_exp_f32_e32 v67, v67
	s_waitcnt vmcnt(1)
	v_pk_mul_f32 v[80:81], v[92:93], v[80:81]
	v_add_f32_e32 v65, 1.0, v65
	v_rcp_f32_e32 v84, v65
	v_add_f32_e32 v65, 1.0, v67
	v_rcp_f32_e32 v85, v65
	v_pk_mul_f32 v[90:91], v[98:99], v[90:91]
	s_waitcnt vmcnt(0)
	v_pk_mul_f32 v[82:83], v[82:83], v[96:97]
	v_pk_mul_f32 v[78:79], v[84:85], v[78:79]
	v_lshlrev_b32_e32 v84, 16, v87
	v_and_b32_e32 v85, 0xffff0000, v87
	v_mul_f32_e32 v65, 0xbfb8aa3b, v84
	v_exp_f32_e32 v65, v65
	v_mul_f32_e32 v67, 0xbfb8aa3b, v85
	v_exp_f32_e32 v67, v67
	v_pk_mul_f32 v[78:79], v[90:91], v[78:79]
	v_add_f32_e32 v65, 1.0, v65
	v_rcp_f32_e32 v86, v65
	v_add_f32_e32 v65, 1.0, v67
	v_rcp_f32_e32 v87, v65
	v_cvt_pk_bf16_f32 v78, v78, v79
	v_pk_mul_f32 v[84:85], v[86:87], v[84:85]
	v_lshlrev_b32_e32 v86, 16, v88
	v_and_b32_e32 v87, 0xffff0000, v88
	v_mul_f32_e32 v65, 0xbfb8aa3b, v86
	v_exp_f32_e32 v65, v65
	v_mul_f32_e32 v67, 0xbfb8aa3b, v87
	v_exp_f32_e32 v67, v67
	v_pk_mul_f32 v[80:81], v[80:81], v[84:85]
	v_add_f32_e32 v65, 1.0, v65
	v_rcp_f32_e32 v84, v65
	v_add_f32_e32 v65, 1.0, v67
	v_rcp_f32_e32 v85, v65
	v_cvt_pk_bf16_f32 v79, v80, v81
	v_pk_mul_f32 v[80:81], v[68:69], v[104:105] op_sel_hi:[0,1]
	v_pk_mul_f32 v[80:81], v[80:81], v[94:95]
	v_pk_mul_f32 v[84:85], v[84:85], v[86:87]
	v_lshlrev_b32_e32 v86, 16, v89
	v_and_b32_e32 v87, 0xffff0000, v89
	v_mul_f32_e32 v65, 0xbfb8aa3b, v86
	v_exp_f32_e32 v65, v65
	v_mul_f32_e32 v67, 0xbfb8aa3b, v87
	v_exp_f32_e32 v67, v67
	v_pk_mul_f32 v[80:81], v[80:81], v[84:85]
	v_add_f32_e32 v65, 1.0, v65
	v_rcp_f32_e32 v84, v65
	v_add_f32_e32 v65, 1.0, v67
	v_rcp_f32_e32 v85, v65
	v_cvt_pk_bf16_f32 v80, v80, v81
	v_pk_mul_f32 v[70:71], v[70:71], v[66:67] op_sel_hi:[1,0]
	v_pk_mul_f32 v[72:73], v[72:73], v[66:67] op_sel_hi:[1,0]
	v_pk_mul_f32 v[84:85], v[84:85], v[86:87]
	v_pk_mul_f32 v[74:75], v[74:75], v[66:67] op_sel_hi:[1,0]
	v_pk_mul_f32 v[82:83], v[82:83], v[84:85]
	v_pk_mul_f32 v[66:67], v[76:77], v[66:67] op_sel_hi:[1,0]
	v_cvt_pk_bf16_f32 v81, v82, v83
	global_store_dwordx4 v[186:187], v[78:81], off offset:192
	s_nop 1
	v_mov_b32_e32 v78, v144
	v_mov_b32_e32 v79, v145
	v_mov_b32_e32 v80, v146
	v_mov_b32_e32 v81, v147
	global_load_dwordx4 v[82:85], v212, s[4:5] offset:448
	global_load_dwordx4 v[86:89], v212, s[4:5] offset:464
	ds_read2st64_b32 v[90:91], v210 offset0:252 offset1:253
	ds_read2st64_b32 v[76:77], v210 offset0:254 offset1:255
	s_waitcnt lgkmcnt(1)
	v_lshlrev_b32_e32 v65, 16, v90
	v_sub_f32_e32 v92, v65, v70
	v_and_b32_e32 v65, 0xffff0000, v90
	v_sub_f32_e32 v93, v65, v72
	s_waitcnt lgkmcnt(0)
	v_lshlrev_b32_e32 v65, 16, v76
	v_sub_f32_e32 v94, v65, v74
	v_and_b32_e32 v65, 0xffff0000, v76
	v_sub_f32_e32 v95, v65, v66
	v_lshlrev_b32_e32 v65, 16, v91
	v_sub_f32_e32 v72, v65, v71
	v_and_b32_e32 v65, 0xffff0000, v91
	v_sub_f32_e32 v73, v65, v73
	v_lshlrev_b32_e32 v65, 16, v77
	v_sub_f32_e32 v66, v65, v75
	v_and_b32_e32 v65, 0xffff0000, v77
	v_sub_f32_e32 v67, v65, v67
	v_permlane32_swap_b32_e32 v92, v94
	v_permlane32_swap_b32_e32 v93, v95
	v_permlane32_swap_b32_e32 v72, v66
	v_permlane32_swap_b32_e32 v73, v67
	s_waitcnt vmcnt(2)
	v_lshlrev_b32_e32 v70, 16, v78
	v_and_b32_e32 v71, 0xffff0000, v78
	v_mul_f32_e32 v65, 0xbfb8aa3b, v70
	v_exp_f32_e32 v65, v65
	v_mul_f32_e32 v69, 0xbfb8aa3b, v71
	v_exp_f32_e32 v69, v69
	v_add_f32_e32 v65, 1.0, v65
	v_rcp_f32_e32 v74, v65
	v_add_f32_e32 v65, 1.0, v69
	v_rcp_f32_e32 v75, v65
	v_pk_mul_f32 v[76:77], v[68:69], v[92:93] op_sel_hi:[0,1]
	s_waitcnt vmcnt(1)
	v_pk_mul_f32 v[76:77], v[76:77], v[82:83]
	v_pk_mul_f32 v[70:71], v[74:75], v[70:71]
	v_lshlrev_b32_e32 v74, 16, v79
	v_and_b32_e32 v75, 0xffff0000, v79
	v_mul_f32_e32 v65, 0xbfb8aa3b, v74
	v_exp_f32_e32 v65, v65
	v_mul_f32_e32 v69, 0xbfb8aa3b, v75
	v_exp_f32_e32 v69, v69
	v_pk_mul_f32 v[70:71], v[76:77], v[70:71]
	v_add_f32_e32 v65, 1.0, v65
	v_rcp_f32_e32 v76, v65
	v_add_f32_e32 v65, 1.0, v69
	v_rcp_f32_e32 v77, v65
	v_pk_mul_f32 v[72:73], v[68:69], v[72:73] op_sel_hi:[0,1]
	v_pk_mul_f32 v[72:73], v[84:85], v[72:73]
	v_cvt_pk_bf16_f32 v70, v70, v71
	v_pk_mul_f32 v[74:75], v[76:77], v[74:75]
	v_lshlrev_b32_e32 v76, 16, v80
	v_and_b32_e32 v77, 0xffff0000, v80
	v_mul_f32_e32 v65, 0xbfb8aa3b, v76
	v_exp_f32_e32 v65, v65
	v_mul_f32_e32 v69, 0xbfb8aa3b, v77
	v_exp_f32_e32 v69, v69
	v_pk_mul_f32 v[72:73], v[72:73], v[74:75]
	v_add_f32_e32 v65, 1.0, v65
	v_rcp_f32_e32 v74, v65
	v_add_f32_e32 v65, 1.0, v69
	v_rcp_f32_e32 v75, v65
	v_cvt_pk_bf16_f32 v71, v72, v73
	v_pk_mul_f32 v[72:73], v[68:69], v[94:95] op_sel_hi:[0,1]
	s_waitcnt vmcnt(0)
	v_pk_mul_f32 v[72:73], v[72:73], v[86:87]
	v_pk_mul_f32 v[74:75], v[74:75], v[76:77]
	v_lshlrev_b32_e32 v76, 16, v81
	v_and_b32_e32 v77, 0xffff0000, v81
	v_mul_f32_e32 v65, 0xbfb8aa3b, v76
	v_exp_f32_e32 v65, v65
	v_mul_f32_e32 v69, 0xbfb8aa3b, v77
	v_exp_f32_e32 v69, v69
	v_pk_mul_f32 v[72:73], v[72:73], v[74:75]
	v_add_f32_e32 v65, 1.0, v65
	v_rcp_f32_e32 v74, v65
	v_add_f32_e32 v65, 1.0, v69
	v_rcp_f32_e32 v75, v65
	v_pk_mul_f32 v[66:67], v[68:69], v[66:67] op_sel_hi:[0,1]
	v_pk_mul_f32 v[66:67], v[66:67], v[88:89]
	v_cvt_pk_bf16_f32 v72, v72, v73
	v_pk_mul_f32 v[68:69], v[74:75], v[76:77]
	s_nop 0
	v_pk_mul_f32 v[66:67], v[66:67], v[68:69]
	s_nop 0
	v_cvt_pk_bf16_f32 v73, v66, v67
	global_store_dwordx4 v[186:187], v[70:73], off offset:224
	s_cbranch_execnz .LBB0_420
	s_branch .LBB0_435
